# SLC: cache union-word and per-lane selection word in registers (reload every 32 tiles); FoX blockDim constant
# baseline (speedup 1.0000x reference)
; template <int MODE, int DK, bool PASS2> ...
;     ...
;         if (MODE == M_FOX) { if (__syncthreads_and(dead ? 1 : 0)) break; }
.LBB0_958:
	v_mov_b32_e32 v4, -1
	s_mov_b32 s10, 0x200
	v_mov_b32_e32 v5, -1
	v_mov_b32_dpp v4, v2 row_shl:1 row_mask:0xf bank_mask:0xf
	v_and_b32_e32 v6, v4, v2
	s_waitcnt lgkmcnt(0)
	s_and_b32 s10, s10, 0xffff
	v_mov_b32_dpp v5, v6 row_shl:2 row_mask:0xf bank_mask:0xf
	v_bitop3_b32 v2, v4, v5, v2 bitop3:0x80
	v_mov_b32_e32 v4, -1
	s_mul_i32 s11, s63, s10
	s_ashr_i32 s11, s11, 8
	v_mov_b32_dpp v4, v2 row_shl:4 row_mask:0xf bank_mask:0xf
	v_bitop3_b32 v5, v6, v4, v5 bitop3:0x80
	v_mov_b32_e32 v6, -1
	s_mul_i32 s11, s11, s29
	s_add_i32 s11, s11, 63
	v_mov_b32_dpp v6, v5 row_shl:8 row_mask:0xf bank_mask:0xf
	v_bitop3_b32 v2, v2, v6, v4 bitop3:0x80
	v_mov_b32_e32 v4, -1
	s_bitcmp1_b32 exec_hi, 0
	s_nop 0
	v_mov_b32_dpp v4, v2 wave_shl:1 row_mask:0xf bank_mask:0xf
	v_mov_b32_e32 v2, -1
	s_nop 1
	v_mov_b32_dpp v2, v4 row_mirror row_mask:0xf bank_mask:0xf
	v_bitop3_b32 v2, v2, v5, v6 bitop3:0x80
	s_nop 0
	v_readlane_b32 s24, v2, 32
	s_cselect_b32 s24, s24, -1
	v_readlane_b32 s46, v2, 0
	s_and_b32 s24, s24, s46
	s_andn2_b32 s11, s11, 63
	s_cmp_eq_u32 s11, 64
	v_mov_b32_e32 v2, s24
	s_cbranch_scc1 .LBB0_937
	v_mad_u64_u32 v[4:5], s[10:11], v1, s10, v[194:195]
	v_lshrrev_b32_e32 v2, 6, v4
	v_or_b32_e32 v2, v2, v206
	v_cmp_eq_u32_e32 vcc, 0, v2
	s_and_saveexec_b64 s[10:11], vcc
	v_mov_b32_e32 v2, s24
	ds_write_b32 v3, v2
	s_or_b64 exec, exec, s[10:11]
	v_cmp_lt_u32_e32 vcc, 63, v4
	s_and_b64 s[50:51], s[6:7], vcc
	s_waitcnt lgkmcnt(0)
	s_barrier
	s_and_saveexec_b64 s[10:11], s[50:51]
	s_cbranch_execz .LBB0_936
	v_mbcnt_lo_u32_b32 v2, exec_lo, 0
	v_mbcnt_hi_u32_b32 v2, exec_hi, v2
	v_cmp_eq_u32_e32 vcc, 0, v2
	s_and_b64 exec, exec, vcc
	s_cbranch_execz .LBB0_936
	v_mov_b32_e32 v2, s24
	ds_and_b32 v3, v2
	s_branch .LBB0_936

; #define LAS __attribute__((address_space(3)))
; __device__ __forceinline__ int otid() { int t = threadIdx.x; asm volatile("" : "+v"(t)); return t; }
; __device__ __forceinline__ int queue_pop(unsigned* qctr, LAS unsigned char* lds) {
;     LAS int* slot = (LAS int*)(lds + LDS_BYTES - 64);
;     __syncthreads();
;     if (otid() == 0) slot[0] = (int)__hip_atomic_fetch_add(qctr, 1u, __ATOMIC_RELAXED, __HIP_MEMORY_SCOPE_AGENT);
;     __syncthreads();
;     return __builtin_amdgcn_readfirstlane(slot[0]);
; }
; template <int ph>
; __device__ __forceinline__ void run_phase(LAS unsigned char* lds, int G, int bid, unsigned* bar_ctr, unsigned& nbar) {
;     ...
;             unsigned* qctr = (unsigned*)(P.ws + WS_BAR) + 389;
;             for (;;) {
;                 const int it = queue_pop(qctr, lds);
;                 if (it >= 512) break;
;                 nsa_item<M_SLC>(P, lds, it & 7, 63 - (it >> 3));
.LBB0_2528:
	s_mov_b32 s100, -1
	s_mov_b32 s101, -1
	v_mov_b32_e32 v1, v171
	s_barrier
	s_nop 0
	v_cmp_eq_u32_e32 vcc, 0, v1
	s_and_saveexec_b64 s[4:5], vcc
	s_cbranch_execz .LBB0_2532
	s_mov_b64 s[28:29], exec
	v_mbcnt_lo_u32_b32 v1, s28, 0
	v_mbcnt_hi_u32_b32 v1, s29, v1
	v_cmp_eq_u32_e32 vcc, 0, v1
	s_and_saveexec_b64 s[6:7], vcc
	s_cbranch_execz .LBB0_2531
	s_bcnt1_i32_b64 s12, s[28:29]
	v_mov_b32_e32 v2, s12
	global_atomic_add v2, v3, v2, s[14:15] sc0

; #define LAS __attribute__((address_space(3)))
; __device__ __forceinline__ int next_sel(const LAS unsigned* un, int j, int hi) {
;     int jj = j + 1;
;     if (jj > hi) return hi + 1;
;     int w = jj >> 5; unsigned mask = un[w] & (~0u << (jj & 31));
;     for (;;) {
;         if (mask) { const int r = w * 32 + __ffs(mask) - 1; return r <= hi ? r : hi + 1; }
;         ++w; if (w > (hi >> 5)) return hi + 1;
;         mask = un[w];
;     }
.LBB0_2587:
	s_add_i32 s4, s48, 1
	s_ashr_i32 s34, s4, 5
	s_lshl_b32 s5, s34, 2
	s_add_i32 s6, s5, 0x100
	s_cmp_eq_u32 s34, s100
	s_cbranch_scc1 .Lslc_unhit
	s_add_i32 s5, s6, 0x12240
	v_mov_b32_e32 v2, s5
	ds_read_b32 v2, v2
	s_mov_b32 s100, s34
	s_waitcnt lgkmcnt(0)
	v_readfirstlane_b32 s99, v2
.Lslc_unhit:
	s_lshl_b32 s4, -1, s4
	s_and_b32 s35, s99, s4
	s_cmp_lg_u32 s35, 0
	s_mov_b64 s[4:5], -1
	s_cbranch_scc0 .LBB0_2589
	s_and_b64 vcc, exec, s[4:5]
	s_mov_b32 s77, s75
	s_cbranch_vccz .LBB0_2595
	s_branch .LBB0_2594

; template <int MODE, int DK, bool PASS2> ...
;     ...
;             if (MODE == M_SLC) {
;                 selbit = ((((const LAS unsigned*)impw)[j >> 5] >> (j & 31)) & 1u) != 0u;
;                 active = active && (__builtin_amdgcn_ballot_w64(selbit) != 0ull);
;             }
;             if (active) {
;                 f32x16 s0, s1;
;                 if (MODE == M_FOX) {
;                     const LAS float* ct = (const LAS float*)(lds + F_CT + buf * 256) + 8 * g;
; #pragma unroll
;                     for (int q4 = 0; q4 < 4; ++q4) {
;                         const f32x4 a = *(const LAS f32x4*)(ct + (q4 >> 1) * 16 + (q4 & 1) * 4), b = *(const LAS f32x4*)(ct + 32 + (q4 >> 1) * 16 + (q4 & 1) * 4);
; #pragma unroll
;                         for (int e = 0; e < 4; ++e) { s0[q4 * 4 + e] = a[e]; s1[q4 * 4 + e] = b[e]; }
;                     }
;                 } else { s0 = (f32x16)(0.f); s1 = (f32x16)(0.f); }
;                 const LAS unsigned char* kb = lds + F_KB0 + buf * F_KBS + g * 16 + prow * KSTR;
;                 __builtin_amdgcn_s_setprio(1);
; #pragma unroll
;                 for (int kk = 0; kk < DK / 16; ++kk) {
;                     const bf16x8 a0 = *(const LAS bf16x8*)(kb + kk * 32);
;                     const bf16x8 a1 = *(const LAS bf16x8*)(kb + 32 * KSTR + kk * 32);
;                     s0 = mfma32(a0, qf[kk], s0); s1 = mfma32(a1, qf[kk], s1);
;                 }
;                 __builtin_amdgcn_s_setprio(0);
;                 const bool need_causal = pos_max > t_wmin;
;                 const bool need_bias = (MODE != M_FOX) && ((t_wmin - pos_max) < 128);
;                 const bool need_win = (MODE == M_WIN) && (t_wmax - pos_min >= 512);
;                 if (!PASS2 && !(need_causal || need_bias || need_win)) {
;                     float mx = fmaxf(s0[0], s1[0]);
; #pragma unroll
;                     for (int r = 1; r < 16; ++r) mx = fmax3(mx, s0[r], s1[r]);
;                     if (MODE == M_SLC) mx = selbit ? mx : NEG;
;                     mx = xhalf_max(mx);
;                     const float mxs = mx * sl2;
;                     const float mn = (mxs > m_run + 8.0f) ? mxs : m_run;
;                     const float alpha = fexp2(m_run - mn);
;                     m_run = mn;
;                     float nm = -mn;
;                     if (MODE == M_SLC) nm = selbit ? nm : -__builtin_inff();
.LBB0_2597:
	s_lshl_b32 s78, s48, 6
	v_cmp_le_i32_e32 vcc, s78, v206
	s_and_saveexec_b64 s[38:39], vcc
	s_cbranch_execz .LBB0_2610
	s_ashr_i32 s4, s48, 5
	s_cmp_eq_u32 s4, s101
	s_cbranch_scc1 .Lslc_selhit
	v_lshl_add_u32 v246, s4, 2, v164
	s_mov_b32 s101, s4
	ds_read_b32 v246, v246
	s_waitcnt lgkmcnt(0)
.Lslc_selhit:
	s_and_b32 s4, s48, 31
	v_lshrrev_b32_e32 v4, s48, v246
	v_bfe_u32 v2, v246, s4, 1
	v_and_b32_e32 v4, 1, v4
	v_cmp_ne_u32_e32 vcc, 0, v2
	v_cmp_eq_u32_e64 s[4:5], 1, v4
	s_cbranch_vccz .LBB0_2610
	s_mul_i32 s6, s74, 0x4400
	s_or_b32 s48, s78, 63
	v_add_u32_e32 v2, s6, v215
	s_setprio 1
	ds_read_b128 v[4:7], v2
	ds_read_b128 v[8:11], v2 offset:32
	s_waitcnt lgkmcnt(1)
	v_mfma_f32_32x32x16_bf16 v[98:113], v[4:7], v[114:117], 0
	ds_read_b128 v[4:7], v2 offset:8704
	ds_read_b128 v[12:15], v2 offset:8736
	s_waitcnt lgkmcnt(1)
	v_mfma_f32_32x32x16_bf16 v[82:97], v[4:7], v[114:117], 0
	v_mfma_f32_32x32x16_bf16 v[98:113], v[8:11], v[118:121], v[98:113]
	ds_read_b128 v[4:7], v2 offset:64
	ds_read_b128 v[8:11], v2 offset:96
	s_waitcnt lgkmcnt(2)
	v_mfma_f32_32x32x16_bf16 v[82:97], v[12:15], v[118:121], v[82:97]
	s_waitcnt lgkmcnt(1)
	v_mfma_f32_32x32x16_bf16 v[98:113], v[4:7], v[122:125], v[98:113]
	ds_read_b128 v[4:7], v2 offset:8768
	ds_read_b128 v[12:15], v2 offset:8800
	s_waitcnt lgkmcnt(1)
	v_mfma_f32_32x32x16_bf16 v[82:97], v[4:7], v[122:125], v[82:97]
	v_mfma_f32_32x32x16_bf16 v[98:113], v[8:11], v[126:129], v[98:113]
	ds_read_b128 v[4:7], v2 offset:128
	ds_read_b128 v[8:11], v2 offset:160
	s_waitcnt lgkmcnt(2)
	v_mfma_f32_32x32x16_bf16 v[82:97], v[12:15], v[126:129], v[82:97]
	s_waitcnt lgkmcnt(1)
	v_mfma_f32_32x32x16_bf16 v[98:113], v[4:7], v[130:133], v[98:113]
	ds_read_b128 v[4:7], v2 offset:8832
	ds_read_b128 v[12:15], v2 offset:8864
	s_waitcnt lgkmcnt(1)
	v_mfma_f32_32x32x16_bf16 v[82:97], v[4:7], v[130:133], v[82:97]
	v_mfma_f32_32x32x16_bf16 v[98:113], v[8:11], v[134:137], v[98:113]
	ds_read_b128 v[4:7], v2 offset:192
	ds_read_b128 v[8:11], v2 offset:224
	s_waitcnt lgkmcnt(2)
	v_mfma_f32_32x32x16_bf16 v[82:97], v[12:15], v[134:137], v[82:97]
	s_waitcnt lgkmcnt(1)
	v_mfma_f32_32x32x16_bf16 v[98:113], v[4:7], v[138:141], v[98:113]
	ds_read_b128 v[4:7], v2 offset:8896
	ds_read_b128 v[12:15], v2 offset:8928
	s_waitcnt lgkmcnt(1)
	v_mfma_f32_32x32x16_bf16 v[82:97], v[4:7], v[138:141], v[82:97]
	v_mfma_f32_32x32x16_bf16 v[98:113], v[8:11], v[142:145], v[98:113]
	s_waitcnt lgkmcnt(0)
	v_mfma_f32_32x32x16_bf16 v[82:97], v[12:15], v[142:145], v[82:97]
	s_setprio 0
	v_min_i32_e32 v2, v199, v207
	v_cmp_gt_i32_e64 s[6:7], s48, v207
	v_cmp_le_i32_e32 vcc, s48, v2
	v_add_f32_e32 v2, 0x41000000, v217
	s_and_saveexec_b64 s[48:49], vcc
	s_xor_b64 s[48:49], exec, s[48:49]
	s_cbranch_execz .LBB0_2603
	s_cmp_eq_u64 s[48:49], 0
	s_cbranch_scc1 .Lfast_slc
	s_nop 3
	v_max_f32_e32 v4, v82, v82
	v_max_f32_e32 v5, v98, v98
	v_max_f32_e32 v4, v5, v4
	v_max3_f32 v4, v4, v99, v83
	s_nop 0
	v_max3_f32 v4, v4, v100, v84
	s_nop 0
	v_max3_f32 v4, v4, v101, v85
	s_nop 0
	v_max3_f32 v4, v4, v102, v86
	s_nop 0
	v_max3_f32 v4, v4, v103, v87
	s_nop 0
	v_max3_f32 v4, v4, v104, v88
	s_nop 0
	v_max3_f32 v4, v4, v105, v89
	s_nop 0
	v_max3_f32 v4, v4, v106, v90
	s_nop 0
	v_max3_f32 v4, v4, v107, v91
	s_nop 0
	v_max3_f32 v4, v4, v108, v92
	s_nop 0
	v_max3_f32 v4, v4, v109, v93
	s_nop 0
	v_max3_f32 v4, v4, v110, v94
	s_nop 0
	v_max3_f32 v4, v4, v111, v95
	s_nop 0
	v_max3_f32 v4, v4, v112, v96
	s_nop 0
	v_max3_f32 v4, v4, v113, v97
	s_nop 0
	v_cndmask_b32_e64 v4, v194, v4, s[4:5]
	v_mov_b32_e32 v5, v4
	s_nop 1
	v_permlane32_swap_b32_e32 v4, v5
	v_max_f32_e32 v5, v5, v5
	v_max_f32_e32 v4, v4, v4
	v_max_f32_e32 v4, v4, v5
	v_mul_f32_e32 v4, 0x3e0293ee, v4
	v_cmp_gt_f32_e32 vcc, v4, v2
	s_nop 1
	v_cndmask_b32_e32 v218, v217, v4, vcc
	v_sub_f32_e32 v2, v217, v218
	v_exp_f32_e32 v2, v2
	s_nop 0
	v_cmp_neq_f32_e32 vcc, 1.0, v2
	s_cbranch_vccz .LBB0_2602
	v_pk_mul_f32 v[80:81], v[80:81], v[2:3] op_sel_hi:[1,0]
	v_pk_mul_f32 v[78:79], v[78:79], v[2:3] op_sel_hi:[1,0]
	v_pk_mul_f32 v[76:77], v[76:77], v[2:3] op_sel_hi:[1,0]
	v_pk_mul_f32 v[74:75], v[74:75], v[2:3] op_sel_hi:[1,0]
	v_pk_mul_f32 v[72:73], v[72:73], v[2:3] op_sel_hi:[1,0]
	v_pk_mul_f32 v[70:71], v[70:71], v[2:3] op_sel_hi:[1,0]
	v_pk_mul_f32 v[68:69], v[68:69], v[2:3] op_sel_hi:[1,0]
	v_pk_mul_f32 v[66:67], v[66:67], v[2:3] op_sel_hi:[1,0]
	v_pk_mul_f32 v[64:65], v[64:65], v[2:3] op_sel_hi:[1,0]
	v_pk_mul_f32 v[62:63], v[62:63], v[2:3] op_sel_hi:[1,0]
	v_pk_mul_f32 v[60:61], v[60:61], v[2:3] op_sel_hi:[1,0]
	v_pk_mul_f32 v[58:59], v[58:59], v[2:3] op_sel_hi:[1,0]
	v_pk_mul_f32 v[56:57], v[56:57], v[2:3] op_sel_hi:[1,0]
	v_pk_mul_f32 v[54:55], v[54:55], v[2:3] op_sel_hi:[1,0]
	v_pk_mul_f32 v[52:53], v[52:53], v[2:3] op_sel_hi:[1,0]
	v_pk_mul_f32 v[50:51], v[50:51], v[2:3] op_sel_hi:[1,0]
	v_pk_mul_f32 v[48:49], v[48:49], v[2:3] op_sel_hi:[1,0]
	v_pk_mul_f32 v[46:47], v[46:47], v[2:3] op_sel_hi:[1,0]
	v_pk_mul_f32 v[44:45], v[44:45], v[2:3] op_sel_hi:[1,0]
	v_pk_mul_f32 v[42:43], v[42:43], v[2:3] op_sel_hi:[1,0]
	v_pk_mul_f32 v[40:41], v[40:41], v[2:3] op_sel_hi:[1,0]
	v_pk_mul_f32 v[38:39], v[38:39], v[2:3] op_sel_hi:[1,0]
	v_pk_mul_f32 v[36:37], v[36:37], v[2:3] op_sel_hi:[1,0]
	v_pk_mul_f32 v[34:35], v[34:35], v[2:3] op_sel_hi:[1,0]
	v_pk_mul_f32 v[32:33], v[32:33], v[2:3] op_sel_hi:[1,0]
	v_pk_mul_f32 v[30:31], v[30:31], v[2:3] op_sel_hi:[1,0]
	v_pk_mul_f32 v[28:29], v[28:29], v[2:3] op_sel_hi:[1,0]
	v_pk_mul_f32 v[26:27], v[26:27], v[2:3] op_sel_hi:[1,0]
	v_pk_mul_f32 v[24:25], v[24:25], v[2:3] op_sel_hi:[1,0]
	v_pk_mul_f32 v[22:23], v[22:23], v[2:3] op_sel_hi:[1,0]
	v_pk_mul_f32 v[20:21], v[20:21], v[2:3] op_sel_hi:[1,0]
	v_pk_mul_f32 v[18:19], v[18:19], v[2:3] op_sel_hi:[1,0]

; #define LAS __attribute__((address_space(3)))
; __global__ void __launch_bounds__(NTHREADS, 2) fwd_megakernel(Params P0) {
;     extern __shared__ __attribute__((aligned(16))) unsigned char shm[];
;     LAS unsigned char* lds = (LAS unsigned char*)shm;
	.amdhsa_kernel _Z14fwd_megakernel6Params
		.amdhsa_group_segment_fixed_size 256
		.amdhsa_private_segment_fixed_size 0
		.amdhsa_kernarg_size 456
		.amdhsa_user_sgpr_count 2
		.amdhsa_user_sgpr_dispatch_ptr 0
		.amdhsa_user_sgpr_queue_ptr 0
		.amdhsa_user_sgpr_kernarg_segment_ptr 1
		.amdhsa_user_sgpr_dispatch_id 0
		.amdhsa_user_sgpr_kernarg_preload_length 0
		.amdhsa_user_sgpr_kernarg_preload_offset 0
		.amdhsa_user_sgpr_private_segment_size 0
		.amdhsa_uses_dynamic_stack 0
		.amdhsa_enable_private_segment 0
		.amdhsa_system_sgpr_workgroup_id_x 1
		.amdhsa_system_sgpr_workgroup_id_y 0
		.amdhsa_system_sgpr_workgroup_id_z 0
		.amdhsa_system_sgpr_workgroup_info 0
		.amdhsa_system_vgpr_workitem_id 2
		.amdhsa_next_free_vgpr 253
		.amdhsa_next_free_sgpr 102
		.amdhsa_accum_offset 256
		.amdhsa_reserve_vcc 1
		.amdhsa_float_round_mode_32 0
		.amdhsa_float_round_mode_16_64 0
		.amdhsa_float_denorm_mode_32 3
		.amdhsa_float_denorm_mode_16_64 3
		.amdhsa_dx10_clamp 1
		.amdhsa_ieee_mode 1
		.amdhsa_fp16_overflow 0
		.amdhsa_tg_split 0
		.amdhsa_exception_fp_ieee_invalid_op 0
		.amdhsa_exception_fp_denorm_src 0
		.amdhsa_exception_fp_ieee_div_zero 0
		.amdhsa_exception_fp_ieee_overflow 0
		.amdhsa_exception_fp_ieee_underflow 0
		.amdhsa_exception_fp_ieee_inexact 0
		.amdhsa_exception_int_div_zero 0
	.end_amdhsa_kernel

; #define LAS __attribute__((address_space(3)))
; #define RUN_PH(n) do { if ((n) >= ph_lo && (n) < ph_hi) { if ((n) != ph_lo) { GSYNC(); } run_phase<(n)>(lds, G, bid, bar_ctr, nbar); \
;                        if ((PROBE_REP >> (n)) & 1u) { GSYNC(); run_phase<(n)>(lds, G, bid, bar_ctr, nbar); } } } while (0)
; __global__ void __launch_bounds__(NTHREADS, 2) fwd_megakernel(Params P0) {
;     extern __shared__ __attribute__((aligned(16))) unsigned char shm[];
;     LAS unsigned char* lds = (LAS unsigned char*)shm;
;     cg::grid_group grid = cg::this_grid();
;     const int G = gridDim.x, bid = blockIdx.x;
;     const int ph_lo = P0.ph_lo, ph_hi = P0.ph_hi;
;     unsigned* bar_ctr = (unsigned*)(P0.ws + WS_BAR); unsigned nbar = 0u;
;     if (ph_hi < 0) grid.sync();
;     RUN_PH(0); RUN_PH(1); RUN_PH(2); RUN_PH(3); RUN_PH(4); RUN_PH(5); RUN_PH(6); RUN_PH(7); RUN_PH(8); RUN_PH(9);
;     RUN_PH(10); RUN_PH(11); RUN_PH(12); RUN_PH(13); RUN_PH(14); RUN_PH(15); RUN_PH(16); RUN_PH(17); RUN_PH(18);
; }
amdhsa.kernels:
  - .agpr_count:     0
    .args:
      - .offset:         0
        .size:           200
        .value_kind:     by_value
      - .offset:         200
        .size:           4
        .value_kind:     hidden_block_count_x
      - .offset:         204
        .size:           4
        .value_kind:     hidden_block_count_y
      - .offset:         208
        .size:           4
        .value_kind:     hidden_block_count_z
      - .offset:         212
        .size:           2
        .value_kind:     hidden_group_size_x
      - .offset:         214
        .size:           2
        .value_kind:     hidden_group_size_y
      - .offset:         216
        .size:           2
        .value_kind:     hidden_group_size_z
      - .offset:         218
        .size:           2
        .value_kind:     hidden_remainder_x
      - .offset:         220
        .size:           2
        .value_kind:     hidden_remainder_y
      - .offset:         222
        .size:           2
        .value_kind:     hidden_remainder_z
      - .offset:         240
        .size:           8
        .value_kind:     hidden_global_offset_x
      - .offset:         248
        .size:           8
        .value_kind:     hidden_global_offset_y
      - .offset:         256
        .size:           8
        .value_kind:     hidden_global_offset_z
      - .offset:         264
        .size:           2
        .value_kind:     hidden_grid_dims
      - .offset:         288
        .size:           8
        .value_kind:     hidden_multigrid_sync_arg
      - .offset:         320
        .size:           4
        .value_kind:     hidden_dynamic_lds_size
    .group_segment_fixed_size: 256
    .kernarg_segment_align: 8
    .kernarg_segment_size: 456
    .language:       OpenCL C
    .language_version:
      - 2
      - 0
    .max_flat_workgroup_size: 512
    .name:           _Z14fwd_megakernel6Params
    .private_segment_fixed_size: 0
    .sgpr_count:     108
    .sgpr_spill_count: 2
    .symbol:         _Z14fwd_megakernel6Params.kd
    .uniform_work_group_size: 1
    .uses_dynamic_stack: false
    .vgpr_count:     253
    .vgpr_spill_count: 0
    .wavefront_size: 64
